# grid barrier: XCD leader invalidates alongside its L2 write-back, waiters poll cross-XCD release word, leader no longer waits on local-generation bump
# baseline (speedup 1.0000x reference)
; __device__ __forceinline__ unsigned xb_add(unsigned* p, unsigned v) { return __hip_atomic_fetch_add(p, v, __ATOMIC_RELAXED, __HIP_MEMORY_SCOPE_AGENT); }
; __device__ __forceinline__ void xcd_barrier(const XcdBarrier& b) {
;     ...
;             xb_add(&bar[XB_XGEN(b.x)], 1u);
;             asm volatile("s_waitcnt vmcnt(0)" ::: "memory");
.LBB0_18:
	s_or_b64 exec, exec, s[8:9]
	s_nop 0

; __device__ __forceinline__ unsigned xb_add(unsigned* p, unsigned v) { return __hip_atomic_fetch_add(p, v, __ATOMIC_RELAXED, __HIP_MEMORY_SCOPE_AGENT); }
; __device__ __forceinline__ void xcd_barrier(const XcdBarrier& b) {
;     ...
;         if (old + 1u == (gen + 1u) * nloc) {
;             __builtin_amdgcn_fence(__ATOMIC_RELEASE, "agent");
;             asm volatile("s_waitcnt vmcnt(0)" ::: "memory");
;             const unsigned og = xb_add(&bar[XB_TOP], 1u);
.LBB0_267:
	s_andn2_saveexec_b64 s[6:7], s[6:7]
	s_cbranch_execz .LBB0_287
	s_mov_b64 s[6:7], exec
	buffer_wbl2 sc1
	buffer_inv sc1
	s_waitcnt lgkmcnt(0)
	s_waitcnt vmcnt(0)
	v_mbcnt_lo_u32_b32 v0, s6, 0
	v_mbcnt_hi_u32_b32 v0, s7, v0
	v_cmp_eq_u32_e32 vcc, 0, v0
	s_and_saveexec_b64 s[8:9], vcc
	s_cbranch_execz .LBB0_270
	s_bcnt1_i32_b64 s6, s[6:7]
	v_mov_b32_e32 v3, s6
	v_readlane_b32 s6, v253, 11
	v_readlane_b32 s7, v253, 12
	s_nop 4
	global_atomic_add v3, v1, v3, s[6:7] sc0

; __device__ __forceinline__ unsigned xb_ld(unsigned* p)              { return __hip_atomic_load(p, __ATOMIC_RELAXED, __HIP_MEMORY_SCOPE_AGENT); }
; __device__ __forceinline__ unsigned xb_add(unsigned* p, unsigned v) { return __hip_atomic_fetch_add(p, v, __ATOMIC_RELAXED, __HIP_MEMORY_SCOPE_AGENT); }
; #define XB_SPIN(cond, bar) do { unsigned _sp = 0; while (cond) { __builtin_amdgcn_s_sleep(1); \
;     if ((++_sp & 255u) == 0u) { if (xb_ld(&(bar)[XB_TMO])) break; if (_sp > XB_SPIN_CAP) { atomicAdd(&(bar)[XB_TMO], 1u); break; } } } } while (0)
; __device__ __forceinline__ void xcd_barrier(const XcdBarrier& b) {
;     ...
;             else XB_SPIN(xb_ld(&bar[XB_TOPGEN]) == tg, bar);
;             __builtin_amdgcn_fence(__ATOMIC_ACQUIRE, "agent");
;             xb_add(&bar[XB_XGEN(b.x)], 1u);
;             asm volatile("s_waitcnt vmcnt(0)" ::: "memory");
.LBB0_284:
	s_or_b64 exec, exec, s[6:7]
	s_mov_b64 s[6:7], exec
	v_mbcnt_lo_u32_b32 v0, s6, 0
	v_mbcnt_hi_u32_b32 v0, s7, v0
	v_cmp_eq_u32_e32 vcc, 0, v0
	s_nop 0
	s_nop 0
	s_and_saveexec_b64 s[8:9], vcc
	s_cbranch_execz .LBB0_286
	s_bcnt1_i32_b64 s6, s[6:7]
	v_mov_b32_e32 v0, s6
	v_readlane_b32 s6, v253, 9
	v_readlane_b32 s7, v253, 10
	s_nop 4
	global_atomic_add v1, v0, s[6:7]

; __device__ __forceinline__ unsigned xb_add(unsigned* p, unsigned v) { return __hip_atomic_fetch_add(p, v, __ATOMIC_RELAXED, __HIP_MEMORY_SCOPE_AGENT); }
; __device__ __forceinline__ void xcd_barrier(const XcdBarrier& b) {
;     ...
;         if (old + 1u == (gen + 1u) * nloc) {
;             __builtin_amdgcn_fence(__ATOMIC_RELEASE, "agent");
;             asm volatile("s_waitcnt vmcnt(0)" ::: "memory");
;             const unsigned og = xb_add(&bar[XB_TOP], 1u);
.LBB0_1607:
	s_andn2_saveexec_b64 s[8:9], s[8:9]
	s_cbranch_execz .LBB0_1627
	s_mov_b64 s[8:9], exec
	buffer_wbl2 sc1
	buffer_inv sc1
	s_waitcnt lgkmcnt(0)
	s_waitcnt vmcnt(0)
	v_mbcnt_lo_u32_b32 v0, s8, 0
	v_mbcnt_hi_u32_b32 v0, s9, v0
	v_cmp_eq_u32_e32 vcc, 0, v0
	s_and_saveexec_b64 s[10:11], vcc
	s_cbranch_execz .LBB0_1610
	s_bcnt1_i32_b64 s8, s[8:9]
	v_mov_b32_e32 v3, s8
	v_readlane_b32 s8, v253, 11
	v_readlane_b32 s9, v253, 12
	s_nop 4
	global_atomic_add v3, v1, v3, s[8:9] sc0

; __device__ __forceinline__ unsigned xb_ld(unsigned* p)              { return __hip_atomic_load(p, __ATOMIC_RELAXED, __HIP_MEMORY_SCOPE_AGENT); }
; __device__ __forceinline__ unsigned xb_add(unsigned* p, unsigned v) { return __hip_atomic_fetch_add(p, v, __ATOMIC_RELAXED, __HIP_MEMORY_SCOPE_AGENT); }
; #define XB_SPIN(cond, bar) do { unsigned _sp = 0; while (cond) { __builtin_amdgcn_s_sleep(1); \
;     if ((++_sp & 255u) == 0u) { if (xb_ld(&(bar)[XB_TMO])) break; if (_sp > XB_SPIN_CAP) { atomicAdd(&(bar)[XB_TMO], 1u); break; } } } } while (0)
; __device__ __forceinline__ void xcd_barrier(const XcdBarrier& b) {
;     ...
;             else XB_SPIN(xb_ld(&bar[XB_TOPGEN]) == tg, bar);
;             __builtin_amdgcn_fence(__ATOMIC_ACQUIRE, "agent");
;             xb_add(&bar[XB_XGEN(b.x)], 1u);
;             asm volatile("s_waitcnt vmcnt(0)" ::: "memory");
.LBB0_1624:
	s_or_b64 exec, exec, s[8:9]
	s_mov_b64 s[8:9], exec
	v_mbcnt_lo_u32_b32 v0, s8, 0
	v_mbcnt_hi_u32_b32 v0, s9, v0
	v_cmp_eq_u32_e32 vcc, 0, v0
	s_nop 0
	s_nop 0
	s_and_saveexec_b64 s[10:11], vcc
	s_cbranch_execz .LBB0_1626
	s_bcnt1_i32_b64 s8, s[8:9]
	v_mov_b32_e32 v0, s8
	v_readlane_b32 s8, v253, 9
	v_readlane_b32 s9, v253, 10
	s_nop 4
	global_atomic_add v1, v0, s[8:9]
.LBB0_1626:
	s_or_b64 exec, exec, s[10:11]
	s_nop 0

; __device__ __forceinline__ unsigned xb_add(unsigned* p, unsigned v) { return __hip_atomic_fetch_add(p, v, __ATOMIC_RELAXED, __HIP_MEMORY_SCOPE_AGENT); }
; __device__ __forceinline__ void xcd_barrier(const XcdBarrier& b) {
;     ...
;         if (old + 1u == (gen + 1u) * nloc) {
;             __builtin_amdgcn_fence(__ATOMIC_RELEASE, "agent");
;             asm volatile("s_waitcnt vmcnt(0)" ::: "memory");
;             const unsigned og = xb_add(&bar[XB_TOP], 1u);
.LBB0_1829:
	s_mov_b64 s[6:7], exec
	buffer_wbl2 sc1
	buffer_inv sc1
	s_waitcnt lgkmcnt(0)
	s_waitcnt vmcnt(0)
	v_mbcnt_lo_u32_b32 v0, s6, 0
	v_mbcnt_hi_u32_b32 v0, s7, v0
	v_cmp_eq_u32_e32 vcc, 0, v0
	s_and_saveexec_b64 s[8:9], vcc
	s_cbranch_execz .LBB0_1831
	s_bcnt1_i32_b64 s6, s[6:7]
	v_mov_b32_e32 v3, s6
	v_readlane_b32 s6, v253, 11
	v_readlane_b32 s7, v253, 12
	s_nop 4
	global_atomic_add v3, v1, v3, s[6:7] sc0

; __device__ __forceinline__ unsigned xb_ld(unsigned* p)              { return __hip_atomic_load(p, __ATOMIC_RELAXED, __HIP_MEMORY_SCOPE_AGENT); }
; __device__ __forceinline__ unsigned xb_add(unsigned* p, unsigned v) { return __hip_atomic_fetch_add(p, v, __ATOMIC_RELAXED, __HIP_MEMORY_SCOPE_AGENT); }
; #define XB_SPIN(cond, bar) do { unsigned _sp = 0; while (cond) { __builtin_amdgcn_s_sleep(1); \
;     if ((++_sp & 255u) == 0u) { if (xb_ld(&(bar)[XB_TMO])) break; if (_sp > XB_SPIN_CAP) { atomicAdd(&(bar)[XB_TMO], 1u); break; } } } } while (0)
; __device__ __forceinline__ void xcd_barrier(const XcdBarrier& b) {
;     ...
;             else XB_SPIN(xb_ld(&bar[XB_TOPGEN]) == tg, bar);
;             __builtin_amdgcn_fence(__ATOMIC_ACQUIRE, "agent");
;             xb_add(&bar[XB_XGEN(b.x)], 1u);
;             asm volatile("s_waitcnt vmcnt(0)" ::: "memory");
.LBB0_1845:
	s_or_b64 exec, exec, s[6:7]
	s_mov_b64 s[6:7], exec
	v_mbcnt_lo_u32_b32 v0, s6, 0
	v_mbcnt_hi_u32_b32 v0, s7, v0
	v_cmp_eq_u32_e32 vcc, 0, v0
	s_nop 0
	s_nop 0
	s_and_saveexec_b64 s[8:9], vcc
	s_cbranch_execnz .LBB0_1846
	s_getpc_b64 s[98:99]
